# attention loop: 79 packed f32 ops split into scalar pairs (7.5 packed-vs-scalar beside MFMAs)
# speedup vs baseline: 1.0027x; 1.0027x over previous
.LBB0_414:
	s_add_u32 s29, s90, s4
	s_addc_u32 s30, s91, s5
	s_lshl_b64 s[4:5], s[6:7], vcc_lo
	s_add_u32 s4, s29, s4
	s_addc_u32 s5, s30, s5
	s_waitcnt vmcnt(16)
	v_lshl_add_u64 v[64:65], v[16:17], 1, s[4:5]
	v_lshl_add_u64 v[16:17], v[18:19], 0, v[68:69]
	s_movk_i32 s29, 0x300
	v_mad_u64_u32 v[24:25], s[4:5], v16, s29, v[86:87]
	v_mov_b32_e32 v16, v25
	v_mul_u32_u24_e32 v66, s28, v68
	v_mad_u64_u32 v[26:27], s[4:5], v17, s29, v[16:17]
	v_lshlrev_b32_e32 v192, 1, v66
	v_mov_b32_e32 v25, v26
	v_lshl_add_u64 v[64:65], v[64:65], 0, v[192:193]
	v_mov_b32_e32 v85, v193
	global_load_dwordx4 v[16:19], v[24:25], off
	global_load_dwordx4 v[20:23], v[24:25], off offset:64
	v_add_co_u32_e32 v24, vcc, s93, v24
	v_lshl_add_u64 v[64:65], v[64:65], 0, v[84:85]
	s_lshl_b32 s78, s28, 5
	v_addc_co_u32_e32 v25, vcc, 0, v26, vcc
	v_lshl_add_u64 v[66:67], v[64:65], 0, s[78:79]
	global_load_dwordx4 v[28:31], v[24:25], off
	s_nop 0
	global_load_dwordx4 v[24:27], v[24:25], off offset:64
	s_nop 0
	global_load_dwordx2 v[134:135], v[64:65], off
	global_load_dwordx2 v[136:137], v[64:65], off offset:32
	global_load_dwordx2 v[130:131], v[66:67], off
	global_load_dwordx2 v[132:133], v[66:67], off offset:32
	v_lshl_add_u64 v[64:65], v[66:67], 0, s[78:79]
	v_lshl_add_u64 v[66:67], v[64:65], 0, s[78:79]
	global_load_dwordx2 v[126:127], v[64:65], off
	global_load_dwordx2 v[128:129], v[64:65], off offset:32
	global_load_dwordx2 v[122:123], v[66:67], off
	global_load_dwordx2 v[124:125], v[66:67], off offset:32
	s_cmp_ge_i32 s71, s94
	s_mov_b64 s[28:29], -1
	s_cbranch_scc0 .LBB0_416
	s_waitcnt vmcnt(12)
	v_mfma_f32_16x16x32_bf16 a[0:3], v[146:149], v[0:3], 0
	v_cmp_lt_i32_e32 vcc, v212, v210
	s_mov_b32 s4, 0x7060302
	s_mov_b64 s[28:29], 0
	v_mfma_f32_16x16x32_bf16 a[0:3], v[142:145], v[4:7], a[0:3]
	v_mfma_f32_16x16x32_bf16 a[8:11], v[146:149], v[8:11], 0
	v_mfma_f32_16x16x32_bf16 a[12:15], v[150:153], v[8:11], 0
	s_nop 5
	s_nop 3
	v_accvgpr_read_b32 v64, a0
	v_accvgpr_read_b32 v65, a1
	v_accvgpr_read_b32 v66, a2
	v_accvgpr_read_b32 v67, a3
	v_mfma_f32_16x16x32_bf16 a[0:3], v[150:153], v[0:3], 0
	v_max_f32_e32 v85, v65, v65
	v_max_f32_e32 v90, v64, v64
	v_max_f32_e32 v85, v90, v85
	v_mfma_f32_16x16x32_bf16 a[0:3], v[138:141], v[4:7], a[0:3]
	v_max_f32_e32 v90, v67, v67
	v_max_f32_e32 v91, v66, v66
	v_max_f32_e32 v90, v91, v90
	v_mfma_f32_16x16x32_bf16 a[8:11], v[142:145], v[12:15], a[8:11]
	v_mfma_f32_16x16x32_bf16 a[12:15], v[138:141], v[12:15], a[12:15]
	s_nop 2
	s_nop 3
	v_accvgpr_read_b32 v154, a2
	v_accvgpr_read_b32 v155, a3
	v_max_f32_e32 v103, v155, v155
	v_max_f32_e32 v156, v154, v154
	v_accvgpr_read_b32 v91, a0
	v_accvgpr_read_b32 v105, a1
	v_max_f32_e32 v103, v156, v103
	v_max3_f32 v103, v91, v105, v103
	v_max3_f32 v85, v85, v90, v103
	v_cndmask_b32_e32 v90, v209, v212, vcc
	v_lshlrev_b32_e32 v90, 2, v90
	ds_bpermute_b32 v103, v90, v85
	v_cmp_lt_i32_e32 vcc, v211, v210
	v_accvgpr_read_b32 v165, a11
	v_accvgpr_read_b32 v173, a15
	v_accvgpr_read_b32 v167, a12
	s_waitcnt lgkmcnt(0)
	v_max_f32_e32 v103, v103, v103
	v_max_f32_e32 v85, v85, v103
	v_cndmask_b32_e32 v103, v209, v211, vcc
	v_lshlrev_b32_e32 v159, 2, v103
	ds_bpermute_b32 v103, v159, v85
	v_accvgpr_read_b32 v169, a13
	s_waitcnt lgkmcnt(0)
	v_max3_f32 v103, v102, v85, v103
	v_sub_f32_e32 v64, v64, v103
	v_mul_f32_e32 v64, 0x3fb8aa3b, v64
	v_exp_f32_e32 v158, v64
	v_sub_f32_e32 v64, v65, v103
	v_mul_f32_e32 v64, 0x3fb8aa3b, v64
	v_exp_f32_e32 v160, v64
	v_sub_f32_e32 v64, v66, v103
	v_mul_f32_e32 v64, 0x3fb8aa3b, v64
	v_exp_f32_e32 v162, v64
	v_sub_f32_e32 v64, v67, v103
	v_mul_f32_e32 v64, 0x3fb8aa3b, v64
	v_exp_f32_e32 v164, v64
	v_sub_f32_e32 v64, v91, v103
	v_mul_f32_e32 v64, 0x3fb8aa3b, v64
	v_exp_f32_e32 v166, v64
	v_sub_f32_e32 v64, v105, v103
	v_sub_f32_e32 v85, v102, v103
	v_mul_f32_e32 v64, 0x3fb8aa3b, v64
	v_mul_f32_e32 v85, 0x3fb8aa3b, v85
	v_exp_f32_e32 v168, v64
	v_sub_f32_e32 v64, v154, v103
	v_sub_f32_e32 v65, v155, v103
	v_mul_f32_e32 v64, 0x3fb8aa3b, v64
	v_exp_f32_e32 v170, v85
	v_mul_f32_e32 v65, 0x3fb8aa3b, v65
	v_exp_f32_e32 v172, v65
	v_exp_f32_e32 v174, v64
	v_mul_f32_e32 v64, v60, v170
	v_mul_f32_e32 v65, v61, v170
	v_mul_f32_e32 v66, v62, v170
	v_mul_f32_e32 v67, v63, v170
	v_cvt_pk_bf16_f32 v156, v166, v168
	v_accvgpr_write_b32 a0, v64
	v_accvgpr_write_b32 a1, v65
	v_accvgpr_write_b32 a2, v66
	v_accvgpr_write_b32 a3, v67
	v_mul_f32_e32 v64, v56, v170
	v_mul_f32_e32 v65, v57, v170
	v_cvt_pk_bf16_f32 v157, v174, v172
	v_mul_f32_e32 v66, v58, v170
	v_mul_f32_e32 v67, v59, v170
	v_accvgpr_read_b32 v85, a8
	v_accvgpr_write_b32 a4, v64
	v_accvgpr_read_b32 v91, a9
	v_cvt_pk_bf16_f32 v155, v162, v164
	v_accvgpr_write_b32 a5, v65
	v_accvgpr_write_b32 a6, v66
	v_accvgpr_write_b32 a7, v67
	v_accvgpr_read_b32 v163, a10
	v_max_f32_e32 v64, v91, v91
	v_max_f32_e32 v65, v85, v85
	v_max_f32_e32 v64, v65, v64
	v_max_f32_e32 v65, v165, v165
	v_max_f32_e32 v66, v163, v163
	v_accvgpr_read_b32 v171, a14
	v_max_f32_e32 v65, v66, v65
	v_max_f32_e32 v66, v173, v173
	v_max_f32_e32 v67, v171, v171
	v_max_f32_e32 v66, v67, v66
	v_max3_f32 v66, v167, v169, v66
	v_max3_f32 v105, v64, v65, v66
	ds_bpermute_b32 v90, v90, v105
	v_mul_f32_e32 v64, v52, v170
	v_mul_f32_e32 v65, v53, v170
	v_mul_f32_e32 v66, v54, v170
	v_mul_f32_e32 v67, v55, v170
	v_accvgpr_write_b32 a8, v64
	v_accvgpr_write_b32 a9, v65
	v_accvgpr_write_b32 a10, v66
	v_accvgpr_write_b32 a11, v67
	s_waitcnt lgkmcnt(0)
	v_max_f32_e32 v64, v90, v90
	v_max_f32_e32 v90, v105, v64
	ds_bpermute_b32 v105, v159, v90
	v_mul_f32_e32 v64, v48, v170
	v_mul_f32_e32 v65, v49, v170
	v_mul_f32_e32 v66, v50, v170
	v_mul_f32_e32 v67, v51, v170
	v_cvt_pk_bf16_f32 v154, v158, v160
	v_accvgpr_write_b32 a12, v64
	s_waitcnt lgkmcnt(0)
	v_max3_f32 v105, v104, v90, v105
	v_accvgpr_write_b32 a13, v65
	v_accvgpr_write_b32 a14, v66
	v_accvgpr_write_b32 a15, v67
	v_sub_f32_e32 v65, v85, v105
	v_mul_f32_e32 v65, 0x3fb8aa3b, v65
	v_sub_f32_e32 v67, v165, v105
	v_exp_f32_e32 v159, v65
	v_sub_f32_e32 v65, v91, v105
	v_mul_f32_e32 v67, 0x3fb8aa3b, v67
	v_mul_f32_e32 v65, 0x3fb8aa3b, v65
	v_exp_f32_e32 v165, v67
	v_sub_f32_e32 v67, v167, v105
	v_exp_f32_e32 v161, v65
	v_sub_f32_e32 v65, v163, v105
	v_mul_f32_e32 v67, 0x3fb8aa3b, v67
	v_mul_f32_e32 v65, 0x3fb8aa3b, v65
	v_exp_f32_e32 v167, v67
	v_sub_f32_e32 v67, v169, v105
	v_exp_f32_e32 v163, v65
	v_mul_f32_e32 v67, 0x3fb8aa3b, v67
	v_sub_f32_e32 v64, v104, v105
	v_exp_f32_e32 v169, v67
	v_sub_f32_e32 v67, v171, v105
	v_mul_f32_e32 v66, 0x3fb8aa3b, v64
	v_add_f32_e32 v64, 0, v158
	v_add_f32_e32 v65, 0, v159
	v_mul_f32_e32 v67, 0x3fb8aa3b, v67
	v_add_f32_e32 v64, v160, v64
	v_add_f32_e32 v65, v161, v65
	v_exp_f32_e32 v175, v67
	v_sub_f32_e32 v67, v173, v105
	v_add_f32_e32 v64, v162, v64
	v_add_f32_e32 v65, v163, v65
	v_mul_f32_e32 v67, 0x3fb8aa3b, v67
	v_exp_f32_e32 v173, v67
	v_exp_f32_e32 v171, v66
	v_add_f32_e32 v64, v164, v64
	v_add_f32_e32 v65, v165, v65
	v_bfe_u32 v164, v159, 16, 1
	v_add_f32_e32 v64, v166, v64
	v_add_f32_e32 v65, v167, v65
	v_mov_b32_e32 v158, v171
	v_add_f32_e32 v64, v168, v64
	v_add_f32_e32 v65, v169, v65
	v_mul_f32_e32 v66, v46, v158
	v_mul_f32_e32 v67, v47, v158
	v_add_f32_e32 v64, v174, v64
	v_add_f32_e32 v65, v175, v65
	v_mfma_f32_16x16x32_bf16 a[0:3], v[118:121], v[154:157], a[0:3]
	v_add_f32_e64 v64, v172, v64
	v_add_f32_e64 v65, v173, v65
	v_fma_f32 v90, v88, v170, v64
	v_fma_f32 v91, v89, v171, v65
	v_mul_f32_e32 v64, v44, v158
	v_mul_f32_e32 v65, v45, v158
	v_add3_u32 v159, v159, v164, s80
	v_accvgpr_write_b32 a16, v64
	v_accvgpr_write_b32 a17, v65
	v_accvgpr_write_b32 a18, v66
	v_accvgpr_write_b32 a19, v67
	v_mul_f32_e32 v64, v40, v158
	v_mul_f32_e32 v65, v41, v158
	v_mul_f32_e32 v66, v42, v158
	v_mul_f32_e32 v67, v43, v158
	v_mfma_f32_16x16x32_bf16 a[4:7], v[114:117], v[154:157], a[4:7]
	v_accvgpr_write_b32 a20, v64
	v_accvgpr_write_b32 a21, v65
	v_accvgpr_write_b32 a22, v66
	v_accvgpr_write_b32 a23, v67
	v_mul_f32_e32 v64, v36, v158
	v_mul_f32_e32 v65, v37, v158
	v_mul_f32_e32 v66, v38, v158
	v_mul_f32_e32 v67, v39, v158
	v_mfma_f32_16x16x32_bf16 a[8:11], v[110:113], v[154:157], a[8:11]
	v_accvgpr_write_b32 a24, v64
	v_bfe_u32 v162, v161, 16, 1
	v_mfma_f32_16x16x32_bf16 a[12:15], v[106:109], v[154:157], a[12:15]
	v_cvt_pk_bf16_f32 v156, v167, v169
	v_accvgpr_write_b32 a25, v65
	v_accvgpr_write_b32 a26, v66
	v_accvgpr_write_b32 a27, v67
	v_mul_f32_e32 v64, v32, v158
	v_mul_f32_e32 v65, v33, v158
	v_add3_u32 v161, v161, v162, s80
	v_mul_f32_e32 v66, v34, v158
	v_mul_f32_e32 v67, v35, v158
	v_cvt_pk_bf16_f32 v157, v175, v173
	v_accvgpr_write_b32 a28, v64
	v_cvt_pk_bf16_f32 v155, v163, v165
	v_perm_b32 v154, v161, v159, s4
	v_accvgpr_write_b32 a29, v65
	v_accvgpr_write_b32 a30, v66
	v_accvgpr_write_b32 a31, v67
	v_mfma_f32_16x16x32_bf16 a[16:19], v[118:121], v[154:157], a[16:19]
	v_mfma_f32_16x16x32_bf16 a[20:23], v[114:117], v[154:157], a[20:23]
	v_mfma_f32_16x16x32_bf16 a[24:27], v[110:113], v[154:157], a[24:27]
	v_mfma_f32_16x16x32_bf16 a[28:31], v[106:109], v[154:157], a[28:31]

.LBB0_436:
	s_nop 5
	v_accvgpr_read_b32 v105, a0
	v_accvgpr_read_b32 v91, a1
	v_accvgpr_read_b32 v90, a2
	v_accvgpr_read_b32 v85, a3
	v_max_f32_e32 v103, v91, v91
	v_max_f32_e32 v154, v105, v105
	v_accvgpr_read_b32 v65, a6
	v_accvgpr_read_b32 v64, a7
	v_max_f32_e32 v103, v154, v103
	v_max_f32_e32 v154, v85, v85
	v_max_f32_e32 v155, v90, v90
	v_max_f32_e32 v154, v155, v154
	v_max_f32_e32 v155, v64, v64
	v_max_f32_e32 v156, v65, v65
	v_accvgpr_read_b32 v67, a4
	v_accvgpr_read_b32 v66, a5
	v_max_f32_e32 v155, v156, v155
	v_max3_f32 v155, v67, v66, v155
	v_cmp_lt_i32_e32 vcc, v212, v210
	v_max3_f32 v103, v103, v154, v155
	s_mov_b32 s4, 0x7060302
	v_cndmask_b32_e32 v154, v209, v212, vcc
	v_lshlrev_b32_e32 v154, 2, v154
	ds_bpermute_b32 v154, v154, v103
	v_cmp_lt_i32_e32 vcc, v211, v210
	s_waitcnt lgkmcnt(0)
	v_max_f32_e32 v154, v154, v154
	v_max_f32_e32 v103, v103, v154
	v_cndmask_b32_e32 v154, v209, v211, vcc
	v_lshlrev_b32_e32 v154, 2, v154
	ds_bpermute_b32 v154, v154, v103
	s_waitcnt lgkmcnt(0)
	v_max3_f32 v103, v102, v103, v154
	v_sub_f32_e32 v105, v105, v103
	v_mul_f32_e32 v105, 0x3fb8aa3b, v105
	v_sub_f32_e32 v91, v91, v103
	v_exp_f32_e32 v105, v105
	v_mul_f32_e32 v91, 0x3fb8aa3b, v91
	v_sub_f32_e32 v90, v90, v103
	v_exp_f32_e32 v91, v91
	v_mul_f32_e32 v90, 0x3fb8aa3b, v90
	v_sub_f32_e32 v85, v85, v103
	v_exp_f32_e32 v90, v90
	v_mul_f32_e32 v85, 0x3fb8aa3b, v85
	v_sub_f32_e32 v67, v67, v103
	v_exp_f32_e32 v85, v85
	v_mul_f32_e32 v67, 0x3fb8aa3b, v67
	v_sub_f32_e32 v66, v66, v103
	v_add_f32_e32 v154, 0, v105
	v_exp_f32_e32 v67, v67
	v_mul_f32_e32 v66, 0x3fb8aa3b, v66
	v_sub_f32_e32 v65, v65, v103
	v_add_f32_e32 v154, v91, v154
	v_exp_f32_e32 v66, v66
	v_mul_f32_e32 v65, 0x3fb8aa3b, v65
	v_sub_f32_e32 v64, v64, v103
	v_sub_f32_e32 v102, v102, v103
	v_add_f32_e32 v154, v90, v154
	v_exp_f32_e32 v65, v65
	v_mul_f32_e32 v64, 0x3fb8aa3b, v64
	v_mul_f32_e32 v102, 0x3fb8aa3b, v102
	v_add_f32_e32 v154, v85, v154
	v_exp_f32_e32 v155, v64
	v_add_f32_e32 v154, v67, v154
	v_exp_f32_e32 v64, v102
	v_add_f32_e32 v154, v66, v154
	v_add_f32_e32 v154, v65, v154
	v_add_f32_e32 v154, v155, v154
	v_fmac_f32_e32 v154, v88, v64
	v_mul_f32_e32 v62, v62, v64
	v_mul_f32_e32 v63, v63, v64
	v_mul_f32_e32 v60, v60, v64
	v_mul_f32_e32 v61, v61, v64
	v_mul_f32_e32 v58, v58, v64
	v_mul_f32_e32 v59, v59, v64
	v_mul_f32_e32 v56, v56, v64
	v_mul_f32_e32 v57, v57, v64
	v_mul_f32_e32 v54, v54, v64
	v_mul_f32_e32 v55, v55, v64
	v_mul_f32_e32 v52, v52, v64
	v_mul_f32_e32 v53, v53, v64
	v_mul_f32_e32 v50, v50, v64
	v_mul_f32_e32 v51, v51, v64
	v_mul_f32_e32 v48, v48, v64
	v_mul_f32_e32 v49, v49, v64
	v_bfe_u32 v64, v155, 16, 1
	v_bfe_u32 v88, v65, 16, 1
	v_cvt_pk_bf16_f32 v66, v67, v66
	v_bfe_u32 v157, v85, 16, 1
	v_bfe_u32 v158, v90, 16, 1
	v_bfe_u32 v159, v91, 16, 1
	v_bfe_u32 v160, v105, 16, 1
	v_add3_u32 v105, v105, v160, s80
	v_add3_u32 v91, v91, v159, s80
	v_add3_u32 v90, v90, v158, s80
	v_add3_u32 v85, v85, v157, s80
	v_add3_u32 v65, v65, v88, s80
	v_add3_u32 v64, v155, v64, s80
	v_accvgpr_write_b32 a0, v60
	v_accvgpr_write_b32 a4, v56
	v_accvgpr_write_b32 a8, v52
	v_accvgpr_write_b32 a12, v48
	v_perm_b32 v67, v64, v65, s4
	v_perm_b32 v65, v85, v90, s4
	v_perm_b32 v64, v91, v105, s4
	v_accvgpr_write_b32 a1, v61
	v_accvgpr_write_b32 a2, v62
	v_accvgpr_write_b32 a3, v63
	v_accvgpr_write_b32 a5, v57
	v_accvgpr_write_b32 a6, v58
	v_accvgpr_write_b32 a7, v59
	v_accvgpr_write_b32 a9, v53
	v_accvgpr_write_b32 a10, v54
	v_accvgpr_write_b32 a11, v55
	v_accvgpr_write_b32 a13, v49
	v_accvgpr_write_b32 a14, v50
	v_accvgpr_write_b32 a15, v51
	v_mfma_f32_16x16x32_bf16 a[0:3], v[118:121], v[64:67], a[0:3]
	v_mov_b32_e32 v88, v154
	v_mfma_f32_16x16x32_bf16 a[4:7], v[114:117], v[64:67], a[4:7]
	v_mfma_f32_16x16x32_bf16 a[8:11], v[110:113], v[64:67], a[8:11]
	v_mfma_f32_16x16x32_bf16 a[12:15], v[106:109], v[64:67], a[12:15]
	s_add_i32 s4, s83, s71
	s_cmp_lt_u32 s4, s33
	s_cbranch_scc0 .LBB0_438
	s_branch .LBB0_457

.LBB0_456:
	s_nop 5
	v_accvgpr_read_b32 v55, a16
	v_accvgpr_read_b32 v54, a17
	v_accvgpr_read_b32 v53, a18
	v_accvgpr_read_b32 v52, a19
	v_max_f32_e32 v56, v54, v54
	v_max_f32_e32 v57, v55, v55
	v_accvgpr_read_b32 v49, a22
	v_accvgpr_read_b32 v48, a23
	v_max_f32_e32 v56, v57, v56
	v_max_f32_e32 v57, v52, v52
	v_max_f32_e32 v58, v53, v53
	v_max_f32_e32 v57, v58, v57
	v_max_f32_e32 v58, v48, v48
	v_max_f32_e32 v59, v49, v49
	v_accvgpr_read_b32 v51, a20
	v_accvgpr_read_b32 v50, a21
	v_max_f32_e32 v58, v59, v58
	v_max3_f32 v58, v51, v50, v58
	v_cmp_lt_i32_e32 vcc, v212, v210
	v_max3_f32 v56, v56, v57, v58
	s_mov_b32 s4, 0x7060302
	v_cndmask_b32_e32 v57, v209, v212, vcc
	v_lshlrev_b32_e32 v57, 2, v57
	ds_bpermute_b32 v57, v57, v56
	v_cmp_lt_i32_e32 vcc, v211, v210
	s_waitcnt lgkmcnt(0)
	v_max_f32_e32 v57, v57, v57
	v_max_f32_e32 v56, v56, v57
	v_cndmask_b32_e32 v57, v209, v211, vcc
	v_lshlrev_b32_e32 v57, 2, v57
	ds_bpermute_b32 v57, v57, v56
	s_waitcnt lgkmcnt(0)
	v_max3_f32 v56, v104, v56, v57
	v_sub_f32_e32 v55, v55, v56
	v_mul_f32_e32 v55, 0x3fb8aa3b, v55
	v_sub_f32_e32 v54, v54, v56
	v_exp_f32_e32 v55, v55
	v_mul_f32_e32 v54, 0x3fb8aa3b, v54
	v_sub_f32_e32 v53, v53, v56
	v_exp_f32_e32 v54, v54
	v_mul_f32_e32 v53, 0x3fb8aa3b, v53
	v_sub_f32_e32 v52, v52, v56
	v_exp_f32_e32 v53, v53
	v_mul_f32_e32 v52, 0x3fb8aa3b, v52
	v_sub_f32_e32 v51, v51, v56
	v_exp_f32_e32 v52, v52
	v_mul_f32_e32 v51, 0x3fb8aa3b, v51
	v_sub_f32_e32 v50, v50, v56
	v_add_f32_e32 v58, 0, v55
	v_exp_f32_e32 v51, v51
	v_mul_f32_e32 v50, 0x3fb8aa3b, v50
	v_sub_f32_e32 v49, v49, v56
	v_add_f32_e32 v58, v54, v58
	v_exp_f32_e32 v50, v50
	v_mul_f32_e32 v49, 0x3fb8aa3b, v49
	v_sub_f32_e32 v48, v48, v56
	v_sub_f32_e32 v57, v104, v56
	v_add_f32_e32 v58, v53, v58
	v_exp_f32_e32 v49, v49
	v_mul_f32_e32 v48, 0x3fb8aa3b, v48
	v_mul_f32_e32 v57, 0x3fb8aa3b, v57
	v_add_f32_e32 v58, v52, v58
	v_exp_f32_e32 v59, v48
	v_add_f32_e32 v58, v51, v58
	v_exp_f32_e32 v48, v57
	v_add_f32_e32 v58, v50, v58
	v_add_f32_e32 v58, v49, v58
	v_add_f32_e32 v58, v59, v58
	v_fmac_f32_e32 v58, v89, v48
	v_mul_f32_e32 v46, v46, v48
	v_mul_f32_e32 v47, v47, v48
	v_mul_f32_e32 v44, v44, v48
	v_mul_f32_e32 v45, v45, v48
	v_mul_f32_e32 v42, v42, v48
	v_mul_f32_e32 v43, v43, v48
	v_mul_f32_e32 v40, v40, v48
	v_mul_f32_e32 v41, v41, v48
	v_mul_f32_e32 v38, v38, v48
	v_mul_f32_e32 v39, v39, v48
	v_mul_f32_e32 v36, v36, v48
	v_mul_f32_e32 v37, v37, v48
	v_mul_f32_e32 v34, v34, v48
	v_mul_f32_e32 v35, v35, v48
	v_mul_f32_e32 v32, v32, v48
	v_mul_f32_e32 v33, v33, v48
	v_bfe_u32 v48, v59, 16, 1
	v_bfe_u32 v57, v49, 16, 1
	v_cvt_pk_bf16_f32 v50, v51, v50
	v_bfe_u32 v62, v52, 16, 1
	v_bfe_u32 v63, v53, 16, 1
	v_bfe_u32 v64, v54, 16, 1
	v_bfe_u32 v65, v55, 16, 1
	v_add3_u32 v55, v55, v65, s80
	v_add3_u32 v54, v54, v64, s80
	v_add3_u32 v53, v53, v63, s80
	v_add3_u32 v52, v52, v62, s80
	v_add3_u32 v49, v49, v57, s80
	v_add3_u32 v48, v59, v48, s80
	v_accvgpr_write_b32 a16, v44
	v_perm_b32 v51, v48, v49, s4
	v_perm_b32 v49, v52, v53, s4
	v_perm_b32 v48, v54, v55, s4
	v_accvgpr_write_b32 a17, v45
	v_accvgpr_write_b32 a18, v46
	v_accvgpr_write_b32 a19, v47
	v_mov_b32_e32 v89, v58
	v_mov_b32_e32 v104, v56
	v_mfma_f32_16x16x32_bf16 a[32:35], v[118:121], v[48:51], a[16:19]
	s_nop 2
	v_accvgpr_write_b32 a16, v40
	v_accvgpr_write_b32 a17, v41
	v_accvgpr_write_b32 a18, v42
	v_accvgpr_write_b32 a19, v43
	s_nop 1
	v_mfma_f32_16x16x32_bf16 a[36:39], v[114:117], v[48:51], a[16:19]
	s_nop 2
	v_accvgpr_write_b32 a16, v36
	v_accvgpr_write_b32 a17, v37
	v_accvgpr_write_b32 a18, v38
	v_accvgpr_write_b32 a19, v39
	s_nop 1
	v_mfma_f32_16x16x32_bf16 a[40:43], v[110:113], v[48:51], a[16:19]
	s_nop 2
	v_accvgpr_write_b32 a16, v32
	v_accvgpr_write_b32 a17, v33
	v_accvgpr_write_b32 a18, v34
	v_accvgpr_write_b32 a19, v35
	s_nop 1
	v_mfma_f32_16x16x32_bf16 a[44:47], v[106:109], v[48:51], a[16:19]

.LBB0_463:
	s_add_u32 s29, s90, vcc_lo
	s_addc_u32 s77, s91, vcc_hi
	s_lshl_b64 s[4:5], s[6:7], s4
	s_add_u32 s4, s29, s4
	s_addc_u32 s5, s77, s5
	v_lshl_add_u64 v[66:67], v[66:67], 0, v[68:69]
	s_movk_i32 s29, 0x300
	v_lshl_add_u64 v[64:65], v[64:65], 1, s[4:5]
	v_mad_u64_u32 v[88:89], s[4:5], v66, s29, v[86:87]
	v_mov_b32_e32 v66, v89
	v_mad_u64_u32 v[66:67], s[4:5], v67, s29, v[66:67]
	v_mov_b32_e32 v89, v66
	global_load_dwordx4 v[146:149], v[88:89], off
	global_load_dwordx4 v[142:145], v[88:89], off offset:64
	v_add_co_u32_e32 v88, vcc, s93, v88
	v_mov_b32_e32 v85, v193
	s_nop 0
	v_addc_co_u32_e32 v89, vcc, 0, v66, vcc
	v_mul_u32_u24_e32 v66, s28, v68
	v_lshlrev_b32_e32 v192, 1, v66
	v_lshl_add_u64 v[64:65], v[64:65], 0, v[192:193]
	v_lshl_add_u64 v[64:65], v[64:65], 0, v[84:85]
	s_lshl_b32 s78, s28, 5
	v_lshl_add_u64 v[66:67], v[64:65], 0, s[78:79]
	global_load_dwordx4 v[150:153], v[88:89], off
	global_load_dwordx4 v[138:141], v[88:89], off offset:64
	global_load_dwordx2 v[118:119], v[64:65], off
	global_load_dwordx2 v[120:121], v[64:65], off offset:32
	global_load_dwordx2 v[114:115], v[66:67], off
	global_load_dwordx2 v[116:117], v[66:67], off offset:32
	v_lshl_add_u64 v[64:65], v[66:67], 0, s[78:79]
	v_lshl_add_u64 v[66:67], v[64:65], 0, s[78:79]
	global_load_dwordx2 v[110:111], v[64:65], off
	global_load_dwordx2 v[112:113], v[64:65], off offset:32
	global_load_dwordx2 v[106:107], v[66:67], off
	global_load_dwordx2 v[108:109], v[66:67], off offset:32
	s_cmp_ge_i32 s31, s76
	s_cbranch_scc1 .LBB0_487
	s_mov_b64 s[28:29], -1
	s_and_b64 vcc, exec, s[26:27]
	s_cbranch_vccz .LBB0_466
	s_waitcnt vmcnt(23)
	v_mfma_f32_16x16x32_bf16 a[32:35], v[16:19], v[0:3], 0
	v_cmp_lt_i32_e32 vcc, v212, v210
	s_mov_b32 s4, 0x7060302
	s_mov_b64 s[28:29], 0
	s_waitcnt vmcnt(22)
	v_mfma_f32_16x16x32_bf16 a[32:35], v[20:23], v[4:7], a[32:35]
	v_mfma_f32_16x16x32_bf16 a[40:43], v[16:19], v[8:11], 0
	s_waitcnt vmcnt(21)
	v_mfma_f32_16x16x32_bf16 a[44:47], v[28:31], v[8:11], 0
	s_nop 4
	s_nop 3
	v_accvgpr_read_b32 v64, a32
	v_accvgpr_read_b32 v65, a33
	v_accvgpr_read_b32 v66, a34
	v_accvgpr_read_b32 v67, a35
	v_mfma_f32_16x16x32_bf16 a[32:35], v[28:31], v[0:3], 0
	v_max_f32_e32 v85, v65, v65
	v_max_f32_e32 v88, v64, v64
	v_max_f32_e32 v85, v88, v85
	s_waitcnt vmcnt(20)
	v_mfma_f32_16x16x32_bf16 a[32:35], v[24:27], v[4:7], a[32:35]
	v_max_f32_e32 v88, v67, v67
	v_max_f32_e32 v89, v66, v66
	v_max_f32_e32 v88, v89, v88
	v_mfma_f32_16x16x32_bf16 a[40:43], v[20:23], v[12:15], a[40:43]
	v_mfma_f32_16x16x32_bf16 a[44:47], v[24:27], v[12:15], a[44:47]
	s_nop 2
	s_nop 3
	v_accvgpr_read_b32 v154, a34
	v_accvgpr_read_b32 v155, a35
	v_max_f32_e32 v102, v155, v155
	v_max_f32_e32 v156, v154, v154
	v_accvgpr_read_b32 v89, a32
	v_accvgpr_read_b32 v104, a33
	v_max_f32_e32 v102, v156, v102
	v_max3_f32 v102, v89, v104, v102
	v_max3_f32 v85, v85, v88, v102
	v_cndmask_b32_e32 v88, v209, v212, vcc
	v_lshlrev_b32_e32 v159, 2, v88
	ds_bpermute_b32 v88, v159, v85
	v_cmp_lt_i32_e32 vcc, v211, v210
	v_accvgpr_read_b32 v167, a43
	v_accvgpr_read_b32 v173, a46
	v_accvgpr_read_b32 v174, a47
	s_waitcnt lgkmcnt(0)
	v_max_f32_e32 v88, v88, v88
	v_max_f32_e32 v85, v85, v88
	v_cndmask_b32_e32 v88, v209, v211, vcc
	v_lshlrev_b32_e32 v161, 2, v88
	ds_bpermute_b32 v88, v161, v85
	v_accvgpr_read_b32 v171, a45
	s_waitcnt lgkmcnt(0)
	v_max3_f32 v102, v103, v85, v88
	v_sub_f32_e32 v64, v64, v102
	v_mul_f32_e32 v64, 0x3fb8aa3b, v64
	v_exp_f32_e32 v88, v64
	v_sub_f32_e32 v64, v65, v102
	v_mul_f32_e32 v64, 0x3fb8aa3b, v64
	v_exp_f32_e32 v158, v64
	v_sub_f32_e32 v64, v66, v102
	v_mul_f32_e32 v64, 0x3fb8aa3b, v64
	v_exp_f32_e32 v160, v64
	v_sub_f32_e32 v64, v67, v102
	v_mul_f32_e32 v64, 0x3fb8aa3b, v64
	v_exp_f32_e32 v162, v64
	v_sub_f32_e32 v64, v89, v102
	v_mul_f32_e32 v64, 0x3fb8aa3b, v64
	v_exp_f32_e32 v164, v64
	v_sub_f32_e32 v64, v104, v102
	v_sub_f32_e32 v85, v103, v102
	v_mul_f32_e32 v64, 0x3fb8aa3b, v64
	v_mul_f32_e32 v85, 0x3fb8aa3b, v85
	v_exp_f32_e32 v166, v64
	v_sub_f32_e32 v64, v154, v102
	v_sub_f32_e32 v65, v155, v102
	v_mul_f32_e32 v64, 0x3fb8aa3b, v64
	v_exp_f32_e32 v168, v85
	v_mul_f32_e32 v65, 0x3fb8aa3b, v65
	v_exp_f32_e32 v170, v65
	v_exp_f32_e32 v172, v64
	v_mul_f32_e32 v64, v60, v168
	v_mul_f32_e32 v65, v61, v168
	v_mul_f32_e32 v66, v62, v168
	v_mul_f32_e32 v67, v63, v168
	v_cvt_pk_bf16_f32 v154, v88, v158
	v_accvgpr_write_b32 a32, v64
	v_accvgpr_write_b32 a33, v65
	v_accvgpr_write_b32 a34, v66
	v_accvgpr_write_b32 a35, v67
	v_mul_f32_e32 v64, v56, v168
	v_mul_f32_e32 v65, v57, v168
	v_cvt_pk_bf16_f32 v157, v172, v170
	v_mul_f32_e32 v66, v58, v168
	v_mul_f32_e32 v67, v59, v168
	v_accvgpr_read_b32 v85, a40
	v_accvgpr_write_b32 a36, v64
	v_accvgpr_read_b32 v163, a41
	v_cvt_pk_bf16_f32 v155, v160, v162
	v_accvgpr_write_b32 a37, v65
	v_accvgpr_write_b32 a38, v66
	v_accvgpr_write_b32 a39, v67
	v_accvgpr_read_b32 v165, a42
	v_max_f32_e32 v64, v163, v163
	v_max_f32_e32 v65, v85, v85
	v_max_f32_e32 v64, v65, v64
	v_max_f32_e32 v65, v167, v167
	v_max_f32_e32 v66, v165, v165
	v_max_f32_e32 v65, v66, v65
	v_max_f32_e32 v66, v174, v174
	v_max_f32_e32 v67, v173, v173
	v_cvt_pk_bf16_f32 v156, v164, v166
	v_accvgpr_read_b32 v169, a44
	v_max_f32_e32 v66, v67, v66
	v_max3_f32 v66, v169, v171, v66
	v_max3_f32 v89, v64, v65, v66
	ds_bpermute_b32 v104, v159, v89
	v_mul_f32_e32 v64, v52, v168
	v_mul_f32_e32 v65, v53, v168
	v_mul_f32_e32 v66, v54, v168
	v_mul_f32_e32 v67, v55, v168
	s_waitcnt vmcnt(18)
	v_mfma_f32_16x16x32_bf16 a[32:35], v[134:137], v[154:157], a[32:35]
	v_accvgpr_write_b32 a40, v64
	v_accvgpr_write_b32 a41, v65
	v_accvgpr_write_b32 a42, v66
	v_accvgpr_write_b32 a43, v67
	s_waitcnt lgkmcnt(0)
	v_max_f32_e32 v64, v104, v104
	v_max_f32_e32 v89, v89, v64
	ds_bpermute_b32 v104, v161, v89
	v_mul_f32_e32 v64, v48, v168
	v_mul_f32_e32 v65, v49, v168
	v_mul_f32_e32 v66, v50, v168
	v_mul_f32_e32 v67, v51, v168
	s_waitcnt vmcnt(16)
	v_mfma_f32_16x16x32_bf16 a[36:39], v[130:133], v[154:157], a[36:39]
	v_accvgpr_write_b32 a44, v64
	s_waitcnt lgkmcnt(0)
	v_max3_f32 v104, v105, v89, v104
	v_accvgpr_write_b32 a45, v65
	v_accvgpr_write_b32 a46, v66
	v_accvgpr_write_b32 a47, v67
	v_sub_f32_e32 v65, v85, v104
	v_mul_f32_e32 v65, 0x3fb8aa3b, v65
	v_exp_f32_e32 v89, v65
	v_sub_f32_e32 v65, v163, v104
	v_mul_f32_e32 v65, 0x3fb8aa3b, v65
	v_exp_f32_e32 v159, v65
	v_sub_f32_e32 v65, v165, v104
	v_mul_f32_e32 v65, 0x3fb8aa3b, v65
	v_exp_f32_e32 v161, v65
	v_sub_f32_e32 v65, v167, v104
	v_mul_f32_e32 v65, 0x3fb8aa3b, v65
	v_exp_f32_e32 v163, v65
	v_sub_f32_e32 v65, v169, v104
	v_mul_f32_e32 v65, 0x3fb8aa3b, v65
	v_exp_f32_e32 v165, v65
	v_sub_f32_e32 v65, v171, v104
	v_mul_f32_e32 v65, 0x3fb8aa3b, v65
	v_exp_f32_e32 v167, v65
	v_sub_f32_e32 v65, v173, v104
	v_sub_f32_e32 v64, v105, v104
	v_mul_f32_e32 v65, 0x3fb8aa3b, v65
	v_mul_f32_e32 v64, 0x3fb8aa3b, v64
	v_exp_f32_e32 v173, v65
	v_sub_f32_e32 v65, v174, v104
	v_mul_f32_e32 v65, 0x3fb8aa3b, v65
	v_exp_f32_e32 v169, v64
	v_exp_f32_e32 v171, v65
	s_waitcnt vmcnt(14)
	v_mfma_f32_16x16x32_bf16 a[40:43], v[126:129], v[154:157], a[40:43]
	v_add_f32_e64 v64, v88, 0
	v_add_f32_e64 v65, v89, 0
	v_mov_b32_e32 v66, v169
	v_add_f32_e32 v64, v158, v64
	v_add_f32_e32 v65, v159, v65
	s_waitcnt vmcnt(12)
	v_mfma_f32_16x16x32_bf16 a[44:47], v[122:125], v[154:157], a[44:47]
	v_mul_f32_e64 v156, v46, v66
	v_mul_f32_e64 v157, v47, v66
	v_mul_f32_e32 v154, v44, v66
	v_mul_f32_e32 v155, v45, v66
	v_bfe_u32 v67, v171, 16, 1
	v_add3_u32 v67, v171, v67, s80
	v_accvgpr_write_b32 a48, v154
	v_accvgpr_write_b32 a49, v155
	v_accvgpr_write_b32 a50, v156
	v_accvgpr_write_b32 a51, v157
	v_mul_f32_e32 v154, v40, v66
	v_mul_f32_e32 v155, v41, v66
	v_add_f32_e32 v64, v160, v64
	v_add_f32_e32 v65, v161, v65
	v_mul_f32_e32 v156, v42, v66
	v_mul_f32_e32 v157, v43, v66
	v_add_f32_e32 v64, v162, v64
	v_add_f32_e32 v65, v163, v65
	v_accvgpr_write_b32 a52, v154
	v_accvgpr_write_b32 a53, v155
	v_accvgpr_write_b32 a54, v156
	v_accvgpr_write_b32 a55, v157
	v_mul_f32_e32 v154, v36, v66
	v_mul_f32_e32 v155, v37, v66
	v_add_f32_e32 v64, v164, v64
	v_add_f32_e32 v65, v165, v65
	v_mul_f32_e32 v156, v38, v66
	v_mul_f32_e32 v157, v39, v66
	v_add_f32_e32 v64, v166, v64
	v_add_f32_e32 v65, v167, v65
	v_accvgpr_write_b32 a56, v154
	v_bfe_u32 v85, v173, 16, 1
	v_bfe_u32 v160, v163, 16, 1
	v_bfe_u32 v162, v161, 16, 1
	v_bfe_u32 v164, v159, 16, 1
	v_bfe_u32 v166, v89, 16, 1
	v_accvgpr_write_b32 a57, v155
	v_accvgpr_write_b32 a58, v156
	v_accvgpr_write_b32 a59, v157
	v_mul_f32_e32 v154, v32, v66
	v_mul_f32_e32 v155, v33, v66
	v_add_f32_e32 v64, v172, v64
	v_add_f32_e32 v65, v173, v65
	v_add3_u32 v89, v89, v166, s80
	v_add3_u32 v164, v159, v164, s80
	v_add3_u32 v159, v161, v162, s80
	v_add3_u32 v162, v163, v160, s80
	v_add3_u32 v85, v173, v85, s80
	v_mul_f32_e32 v156, v34, v66
	v_mul_f32_e32 v157, v35, v66
	v_add_f32_e32 v64, v170, v64
	v_add_f32_e32 v65, v171, v65
	v_accvgpr_write_b32 a60, v154
	v_perm_b32 v161, v67, v85, s4
	v_cvt_pk_bf16_f32 v160, v165, v167
	v_perm_b32 v159, v162, v159, s4
	v_perm_b32 v158, v164, v89, s4
	v_accvgpr_write_b32 a61, v155
	v_accvgpr_write_b32 a62, v156
	v_accvgpr_write_b32 a63, v157
	v_fma_f32 v64, v90, v168, v64
	v_fma_f32 v65, v91, v169, v65
	v_mfma_f32_16x16x32_bf16 a[48:51], v[134:137], v[158:161], a[48:51]
	v_mfma_f32_16x16x32_bf16 a[52:55], v[130:133], v[158:161], a[52:55]
	v_mfma_f32_16x16x32_bf16 a[56:59], v[126:129], v[158:161], a[56:59]
	v_mfma_f32_16x16x32_bf16 a[60:63], v[122:125], v[158:161], a[60:63]

.LBB0_486:
	s_nop 4
	v_accvgpr_read_b32 v104, a0
	v_accvgpr_read_b32 v89, a1
	v_accvgpr_read_b32 v88, a2
	v_accvgpr_read_b32 v85, a3
	v_max_f32_e32 v102, v89, v89
	v_max_f32_e32 v154, v104, v104
	v_accvgpr_read_b32 v65, a6
	v_accvgpr_read_b32 v64, a7
	v_max_f32_e32 v102, v154, v102
	v_max_f32_e32 v154, v85, v85
	v_max_f32_e32 v155, v88, v88
	v_max_f32_e32 v154, v155, v154
	v_max_f32_e32 v155, v64, v64
	v_max_f32_e32 v156, v65, v65
	v_accvgpr_read_b32 v67, a4
	v_accvgpr_read_b32 v66, a5
	v_max_f32_e32 v155, v156, v155
	v_max3_f32 v155, v67, v66, v155
	v_cmp_lt_i32_e32 vcc, v212, v210
	v_max3_f32 v102, v102, v154, v155
	s_mov_b32 s4, 0x7060302
	v_cndmask_b32_e32 v154, v209, v212, vcc
	v_lshlrev_b32_e32 v154, 2, v154
	ds_bpermute_b32 v154, v154, v102
	v_cmp_lt_i32_e32 vcc, v211, v210
	s_waitcnt lgkmcnt(0)
	v_max_f32_e32 v154, v154, v154
	v_max_f32_e32 v102, v102, v154
	v_cndmask_b32_e32 v154, v209, v211, vcc
	v_lshlrev_b32_e32 v154, 2, v154
	ds_bpermute_b32 v154, v154, v102
	s_waitcnt lgkmcnt(0)
	v_max3_f32 v102, v103, v102, v154
	v_sub_f32_e32 v104, v104, v102
	v_mul_f32_e32 v104, 0x3fb8aa3b, v104
	v_sub_f32_e32 v89, v89, v102
	v_exp_f32_e32 v104, v104
	v_mul_f32_e32 v89, 0x3fb8aa3b, v89
	v_sub_f32_e32 v88, v88, v102
	v_exp_f32_e32 v89, v89
	v_mul_f32_e32 v88, 0x3fb8aa3b, v88
	v_sub_f32_e32 v85, v85, v102
	v_exp_f32_e32 v88, v88
	v_mul_f32_e32 v85, 0x3fb8aa3b, v85
	v_sub_f32_e32 v67, v67, v102
	v_exp_f32_e32 v85, v85
	v_mul_f32_e32 v67, 0x3fb8aa3b, v67
	v_sub_f32_e32 v66, v66, v102
	v_add_f32_e32 v154, 0, v104
	v_exp_f32_e32 v67, v67
	v_mul_f32_e32 v66, 0x3fb8aa3b, v66
	v_sub_f32_e32 v65, v65, v102
	v_add_f32_e32 v154, v89, v154
	v_exp_f32_e32 v66, v66
	v_mul_f32_e32 v65, 0x3fb8aa3b, v65
	v_sub_f32_e32 v64, v64, v102
	v_sub_f32_e32 v103, v103, v102
	v_add_f32_e32 v154, v88, v154
	v_exp_f32_e32 v65, v65
	v_mul_f32_e32 v64, 0x3fb8aa3b, v64
	v_mul_f32_e32 v103, 0x3fb8aa3b, v103
	v_add_f32_e32 v154, v85, v154
	v_exp_f32_e32 v155, v64
	v_add_f32_e32 v154, v67, v154
	v_exp_f32_e32 v64, v103
	v_add_f32_e32 v154, v66, v154
	v_add_f32_e32 v154, v65, v154
	v_add_f32_e32 v154, v155, v154
	v_fmac_f32_e32 v154, v90, v64
	v_mul_f32_e32 v62, v62, v64
	v_mul_f32_e32 v63, v63, v64
	v_mul_f32_e32 v60, v60, v64
	v_mul_f32_e32 v61, v61, v64
	v_mul_f32_e32 v58, v58, v64
	v_mul_f32_e32 v59, v59, v64
	v_mul_f32_e32 v56, v56, v64
	v_mul_f32_e32 v57, v57, v64
	v_mul_f32_e32 v54, v54, v64
	v_mul_f32_e32 v55, v55, v64
	v_mul_f32_e32 v52, v52, v64
	v_mul_f32_e32 v53, v53, v64
	v_mul_f32_e32 v50, v50, v64
	v_mul_f32_e32 v51, v51, v64
	v_mul_f32_e32 v48, v48, v64
	v_mul_f32_e32 v49, v49, v64
	v_bfe_u32 v64, v155, 16, 1
	v_bfe_u32 v90, v65, 16, 1
	v_cvt_pk_bf16_f32 v66, v67, v66
	v_bfe_u32 v157, v85, 16, 1
	v_bfe_u32 v158, v88, 16, 1
	v_bfe_u32 v159, v89, 16, 1
	v_bfe_u32 v160, v104, 16, 1
	v_add3_u32 v104, v104, v160, s80
	v_add3_u32 v89, v89, v159, s80
	v_add3_u32 v88, v88, v158, s80
	v_add3_u32 v85, v85, v157, s80
	v_add3_u32 v65, v65, v90, s80
	v_add3_u32 v64, v155, v64, s80
	v_accvgpr_write_b32 a0, v60
	v_perm_b32 v67, v64, v65, s4
	v_perm_b32 v65, v85, v88, s4
	v_perm_b32 v64, v89, v104, s4
	v_accvgpr_write_b32 a1, v61
	v_accvgpr_write_b32 a2, v62
	v_accvgpr_write_b32 a3, v63
	v_mov_b32_e32 v90, v154
	s_waitcnt vmcnt(18)
	v_mfma_f32_16x16x32_bf16 a[32:35], v[134:137], v[64:67], a[0:3]
	s_nop 2
	v_accvgpr_write_b32 a0, v56
	v_accvgpr_write_b32 a1, v57
	v_accvgpr_write_b32 a2, v58
	v_accvgpr_write_b32 a3, v59
	s_waitcnt vmcnt(16)
	s_nop 0
	v_mfma_f32_16x16x32_bf16 a[36:39], v[130:133], v[64:67], a[0:3]
	s_nop 2
	v_accvgpr_write_b32 a0, v52
	v_accvgpr_write_b32 a1, v53
	v_accvgpr_write_b32 a2, v54
	v_accvgpr_write_b32 a3, v55
	s_waitcnt vmcnt(14)
	s_nop 0
	v_mfma_f32_16x16x32_bf16 a[40:43], v[126:129], v[64:67], a[0:3]
	s_nop 2
	v_accvgpr_write_b32 a0, v48
	v_accvgpr_write_b32 a1, v49
	v_accvgpr_write_b32 a2, v50
	v_accvgpr_write_b32 a3, v51
	s_waitcnt vmcnt(12)
	s_nop 0
	v_mfma_f32_16x16x32_bf16 a[44:47], v[122:125], v[64:67], a[0:3]
	s_add_i32 s4, s83, s71
	s_add_i32 s4, s4, 1
	s_cmp_lt_u32 s4, s33
	s_cbranch_scc0 .LBB0_489
	s_branch .LBB0_508

.LBB0_507:
	s_nop 4
	v_accvgpr_read_b32 v23, a0
	v_accvgpr_read_b32 v22, a1
	v_accvgpr_read_b32 v21, a2
	v_accvgpr_read_b32 v20, a3
	v_max_f32_e32 v24, v22, v22
	v_max_f32_e32 v25, v23, v23
	v_accvgpr_read_b32 v17, a6
	v_accvgpr_read_b32 v16, a7
	v_max_f32_e32 v24, v25, v24
	v_max_f32_e32 v25, v20, v20
	v_max_f32_e32 v26, v21, v21
	v_max_f32_e32 v25, v26, v25
	v_max_f32_e32 v26, v16, v16
	v_max_f32_e32 v27, v17, v17
	v_accvgpr_read_b32 v19, a4
	v_accvgpr_read_b32 v18, a5
	v_max_f32_e32 v26, v27, v26
	v_max3_f32 v26, v19, v18, v26
	v_cmp_lt_i32_e32 vcc, v212, v210
	v_max3_f32 v24, v24, v25, v26
	s_mov_b32 s4, 0x7060302
	v_cndmask_b32_e32 v25, v209, v212, vcc
	v_lshlrev_b32_e32 v25, 2, v25
	ds_bpermute_b32 v25, v25, v24
	v_cmp_lt_i32_e32 vcc, v211, v210
	s_waitcnt lgkmcnt(0)
	v_max_f32_e32 v25, v25, v25
	v_max_f32_e32 v24, v24, v25
	v_cndmask_b32_e32 v25, v209, v211, vcc
	v_lshlrev_b32_e32 v25, 2, v25
	ds_bpermute_b32 v25, v25, v24
	s_waitcnt lgkmcnt(0)
	v_max3_f32 v48, v105, v24, v25
	v_sub_f32_e32 v23, v23, v48
	v_mul_f32_e32 v23, 0x3fb8aa3b, v23
	v_sub_f32_e32 v22, v22, v48
	v_exp_f32_e32 v49, v23
	v_mul_f32_e32 v22, 0x3fb8aa3b, v22
	v_sub_f32_e32 v21, v21, v48
	v_exp_f32_e32 v50, v22
	v_mul_f32_e32 v21, 0x3fb8aa3b, v21
	v_sub_f32_e32 v20, v20, v48
	v_exp_f32_e32 v51, v21
	v_mul_f32_e32 v20, 0x3fb8aa3b, v20
	v_sub_f32_e32 v19, v19, v48
	v_exp_f32_e32 v52, v20
	v_mul_f32_e32 v19, 0x3fb8aa3b, v19
	v_sub_f32_e32 v18, v18, v48
	v_add_f32_e32 v23, 0, v49
	v_exp_f32_e32 v53, v19
	v_mul_f32_e32 v18, 0x3fb8aa3b, v18
	v_sub_f32_e32 v17, v17, v48
	v_add_f32_e32 v22, v50, v23
	v_exp_f32_e32 v54, v18
	v_mul_f32_e32 v17, 0x3fb8aa3b, v17
	v_sub_f32_e32 v16, v16, v48
	v_sub_f32_e32 v24, v105, v48
	v_add_f32_e32 v21, v51, v22
	v_exp_f32_e32 v55, v17
	v_mul_f32_e32 v16, 0x3fb8aa3b, v16
	v_mul_f32_e32 v24, 0x3fb8aa3b, v24
	v_add_f32_e32 v20, v52, v21
	v_exp_f32_e32 v56, v16
	v_add_f32_e32 v19, v53, v20
	v_exp_f32_e32 v28, v24
	v_add_f32_e32 v18, v54, v19
	v_add_f32_e32 v17, v55, v18
	v_add_f32_e32 v57, v56, v17
	v_fmac_f32_e32 v57, v91, v28
	v_mul_f32_e32 v18, v46, v28
	v_mul_f32_e32 v19, v47, v28
	v_mul_f32_e32 v16, v44, v28
	v_mul_f32_e32 v17, v45, v28
	v_mul_f32_e32 v22, v42, v28
	v_mul_f32_e32 v23, v43, v28
	v_mul_f32_e32 v20, v40, v28
	v_mul_f32_e32 v21, v41, v28
	v_mul_f32_e32 v26, v38, v28
	v_mul_f32_e32 v27, v39, v28
	v_mul_f32_e32 v24, v36, v28
	v_mul_f32_e32 v25, v37, v28
	v_mul_f32_e32 v30, v34, v28
	v_mul_f32_e32 v31, v35, v28
	v_mul_f32_e32 v29, v33, v28
	v_mul_f32_e32 v28, v32, v28
	v_cvt_pk_bf16_f32 v34, v53, v54
	v_accvgpr_write_b32 a0, v16
	v_cvt_pk_bf16_f32 v35, v55, v56
	v_cvt_pk_bf16_f32 v33, v51, v52
	v_cvt_pk_bf16_f32 v32, v49, v50
	v_accvgpr_write_b32 a1, v17
	v_accvgpr_write_b32 a2, v18
	v_accvgpr_write_b32 a3, v19
	v_mov_b32_e32 v91, v57
	v_mov_b32_e32 v105, v48
	s_waitcnt vmcnt(18)
	v_mfma_f32_16x16x32_bf16 a[16:19], v[134:137], v[32:35], a[0:3]
	s_nop 2
	v_accvgpr_write_b32 a0, v20
	v_accvgpr_write_b32 a1, v21
	v_accvgpr_write_b32 a2, v22
	v_accvgpr_write_b32 a3, v23
	s_waitcnt vmcnt(16)
	s_nop 0
	v_mfma_f32_16x16x32_bf16 a[20:23], v[130:133], v[32:35], a[0:3]
	s_nop 2
	v_accvgpr_write_b32 a0, v24
	v_accvgpr_write_b32 a1, v25
	v_accvgpr_write_b32 a2, v26
	v_accvgpr_write_b32 a3, v27
	s_waitcnt vmcnt(14)
	s_nop 0
	v_mfma_f32_16x16x32_bf16 a[24:27], v[126:129], v[32:35], a[0:3]
	s_nop 2
	v_accvgpr_write_b32 a0, v28
	v_accvgpr_write_b32 a1, v29
	v_accvgpr_write_b32 a2, v30
	v_accvgpr_write_b32 a3, v31
	s_waitcnt vmcnt(12)
	s_nop 0
	v_mfma_f32_16x16x32_bf16 a[28:31], v[122:125], v[32:35], a[0:3]
